# P9 SwiGLU-up GEMM: stagger workgroup start by (blockIdx>>3)&3 x ~6us to desynchronise tile-boundary bursts
# speedup vs baseline: 1.0001x; 1.0001x over previous
; __device__ __forceinline__ int lane_id_fresh() { int l; asm volatile("v_mbcnt_lo_u32_b32 %0, -1, 0\n\tv_mbcnt_hi_u32_b32 %0, -1, %0" : "=v"(l)); return l; }
; #define PG8_STAGE(bufoff, gbase, voff) do { _Pragma("unroll") for (int _i = 0; _i < 2; ++_i) \
;         __builtin_amdgcn_global_load_lds((const unsigned*)((const char*)(gbase) + (voff)[_i]), (PG8_LAS unsigned*)(lds + (bufoff) + ldsw + _i * 8192), 16, 0, 0); } while (0)
; #define PG8_BAR __builtin_amdgcn_s_barrier()
; template <class Epi, class Sched, bool ALIGN_EPI = false, bool SP2 = false>
; __device__ __forceinline__ void gemm_phase(PG8_LAS unsigned char* lds, const Gemm g, const Sched& S, const Epi& E, int wave_in) {
;     const int wid = wave_in, lane = lane_id_fresh(), tid = wid * 64 + lane, wr = wid >> 2, wc = wid & 3, fr = lane & 15, fq = lane >> 4;
;     const int K = g.K, nt = K / BK;
;     unsigned voffA[2], voffB[2];
; #pragma unroll
;     for (int i = 0; i < 2; ++i) { int R, C; stage_rc(tid * 16 + i * 8192, R, C); const int Rb = Epi::PERM ? ((R & ~31) + perm32(R & 31)) : R;
;         voffA[i] = (unsigned)(R * g.lda + C) * 2u; voffB[i] = (unsigned)(Rb * K + C) * 2u; }
;     const size_t kstep = (size_t)(BK * 2);
;     const size_t hstepA = (size_t)HALF * g.lda * 2, hstepB = (size_t)HALF * K * 2;
;     const size_t tstepA = 2 * hstepA, tstepB = 2 * hstepB;
;     const unsigned ldsw = (unsigned)wid * 1024u;
;     const int aoff = lds_byte(wr * 64 + fr, fq * 8), boff = lds_byte(wc * 32 + fr, fq * 8);
;     ...
;     Unit cur, nxt; int ui = 0;
;     if (!S.next(0, cur)) return;
;     f32x4 acc[2][2][4][2];
; #pragma unroll
;     for (int a = 0; a < 2; ++a)
; #pragma unroll
;         for (int b = 0; b < 2; ++b)
; #pragma unroll
;             for (int m = 0; m < 4; ++m)
; #pragma unroll
;                 for (int n = 0; n < 2; ++n) acc[a][b][m][n] = (f32x4){0.f, 0.f, 0.f, 0.f};
;     bf16x8 At[4][2], B0[2][2], B1[2][2];
;     const char* cA = (const char*)g.A + (size_t)cur.pm * tstepA; const char* cB = (const char*)g.Bt + (size_t)cur.pn * tstepB;
;     S.a_ready(cur);
;     if constexpr (SP2) {
;         PG8_STAGE(PG8_SB(0, 0), cB, voffB); PG8_STAGE(PG8_SB(0, 1), cB + hstepB, voffB); PG8_STAGE(PG8_SA(0, 0), cA, voffA); PG8_STAGE(PG8_SA(0, 1), cA + hstepA, voffA);
;         if (wr == 1) PG8_BAR;
.LBB0_826:
	s_or_b64 exec, exec, s[0:1]
	s_cmpk_lt_i32 s68, 0xb00
	s_waitcnt lgkmcnt(0)
	s_barrier
	v_mbcnt_lo_u32_b32 v14, -1, 0
	v_mbcnt_hi_u32_b32 v14, -1, v14
	s_cbranch_scc0 .LBB0_842
	s_bfe_u32 s98, s88, 0x20003
	s_cmp_eq_u32 s98, 0
	s_cbranch_scc1 .Lnostag_p9
.Lstag_p9:
	s_sleep 127
	s_sleep 64
	s_sub_u32 s98, s98, 1
	s_cmp_lg_u32 s98, 0
	s_cbranch_scc1 .Lstag_p9
.Lnostag_p9:
	v_lshl_add_u32 v0, v14, 4, s33
	v_add_u32_e32 v1, 0x2000, v0
	v_ashrrev_i32_e32 v2, 31, v1
	v_lshrrev_b32_e32 v2, 22, v2
	v_add_u32_e32 v2, v1, v2
	v_ashrrev_i32_e32 v8, 10, v2
	v_mul_i32_i24_e32 v2, 0x400, v8
	v_sub_u32_e32 v1, v1, v2
	v_lshrrev_b32_e32 v2, 4, v1
	v_bitop3_b32 v1, v2, v1, 32 bitop3:0x6c
	v_ashrrev_i32_e32 v2, 31, v1
	v_lshrrev_b32_e32 v2, 26, v2
	v_add_u32_e32 v2, v1, v2
	v_ashrrev_i32_e32 v9, 6, v2
	v_lshlrev_b32_e32 v3, 3, v8
	v_and_b32_e32 v2, 0xffc0, v2
	v_and_b32_e32 v3, -16, v3
	v_sub_u32_e32 v1, v1, v2
	v_add_u32_e32 v3, v9, v3
	v_lshrrev_b16_e32 v2, 7, v1
	v_and_b32_e32 v4, 3, v9
	s_mov_b32 s0, 0x1fffe0
	v_lshrrev_b32_e32 v5, 2, v3
	v_lshlrev_b32_e32 v6, 1, v3
	v_and_b32_e32 v2, 1, v2
	v_and_or_b32 v4, v3, s0, v4
	v_and_b32_e32 v5, 4, v5
	v_and_b32_e32 v6, 24, v6
	v_add_u16_e32 v1, v1, v2
	v_mov_b32_e32 v2, 1
	v_or3_b32 v4, v4, v5, v6
	v_lshlrev_b32_e32 v5, 5, v8
	v_ashrrev_i16_sdwa v1, v2, sext(v1) dst_sel:DWORD dst_unused:UNUSED_PAD src0_sel:DWORD src1_sel:BYTE_0
	v_and_b32_e32 v5, 32, v5
	v_bfe_i32 v10, v1, 0, 16
	v_add_lshl_u32 v1, v5, v10, 1
	v_lshl_add_u32 v128, v4, 11, v1
	v_lshl_add_u32 v130, v3, 11, v1
	v_ashrrev_i32_e32 v1, 31, v0
	v_lshrrev_b32_e32 v1, 22, v1
	v_add_u32_e32 v1, v0, v1
	v_ashrrev_i32_e32 v11, 10, v1
	v_mul_i32_i24_e32 v1, 0x400, v11
	v_sub_u32_e32 v0, v0, v1
	v_lshrrev_b32_e32 v1, 4, v0
	v_bitop3_b32 v0, v1, v0, 32 bitop3:0x6c
	v_ashrrev_i32_e32 v1, 31, v0
	v_lshrrev_b32_e32 v1, 26, v1
	v_add_u32_e32 v1, v0, v1
	v_lshlrev_b32_e32 v3, 3, v11
	s_add_u32 s2, s28, 0xe00000
	v_ashrrev_i32_e32 v12, 6, v1
	v_and_b32_e32 v3, -16, v3
	s_addc_u32 s3, s29, 0
	v_add_u32_e32 v3, v12, v3
	v_and_b32_e32 v4, 3, v12
	v_and_or_b32 v4, v3, s0, v4
	s_movk_i32 s34, 0x161
	s_and_b64 s[0:1], s[4:5], exec
	s_cselect_b32 s0, s34, 0x160
	s_mul_i32 s0, s47, s0
	s_add_i32 s0, s0, s38
	s_mul_hi_i32 s1, s0, 0x2e8ba2e9
	s_lshr_b32 s8, s1, 31
	s_ashr_i32 s1, s1, 5
	s_add_i32 s1, s1, s8
	s_lshl_b32 s8, s1, 3
	s_mulk_i32 s1, 0xb0
	s_sub_i32 s1, s0, s1
	s_bfe_u32 s0, s1, 0x3001c
	s_add_i32 s9, s1, s0
	s_sext_i32_i16 s0, s9
	s_and_b32 s9, s9, 0xfff8
	s_sub_i32 s1, s1, s9
	s_sext_i32_i16 s1, s1
	v_lshrrev_b32_e32 v5, 2, v3
	v_lshlrev_b32_e32 v6, 1, v3
	v_and_b32_e32 v1, 0xc0, v1
	s_lshr_b32 s0, s0, 3
	s_add_i32 s18, s8, s1
	v_and_b32_e32 v5, 4, v5
	v_and_b32_e32 v6, 24, v6
	v_sub_u32_e32 v0, v0, v1
	s_ashr_i32 s19, s18, 31
	s_bfe_i64 s[10:11], s[0:1], 0x100000
	v_or3_b32 v4, v4, v5, v6
	v_lshlrev_b32_e32 v5, 5, v11
	v_ashrrev_i16_sdwa v0, v2, sext(v0) dst_sel:DWORD dst_unused:UNUSED_PAD src0_sel:DWORD src1_sel:BYTE_0
	s_lshl_b64 s[8:9], s[18:19], 19
	s_lshl_b64 s[10:11], s[10:11], 19
	v_and_b32_e32 v5, 32, v5
	v_bfe_i32 v13, v0, 0, 16
	s_add_u32 s22, s2, s10
	v_add_lshl_u32 v0, v5, v13, 1
	s_addc_u32 s23, s3, s11
	s_add_i32 s35, s33, 0
	v_lshl_add_u32 v132, v4, 11, v0
	s_add_i32 m0, s35, 0x10000
	v_lshl_add_u32 v134, v3, 11, v0
	global_load_lds_dwordx4 v132, s[22:23]
	s_add_i32 m0, s35, 0x12000
	s_add_u32 s10, s22, 0x40000
	global_load_lds_dwordx4 v128, s[22:23]
	s_addc_u32 s11, s23, 0
	s_add_i32 m0, s35, 0x14000
	v_mov_b32_e32 v133, 0
	global_load_lds_dwordx4 v132, s[10:11]
	s_add_i32 m0, s35, 0x16000
	v_mov_b32_e32 v129, v133
	global_load_lds_dwordx4 v128, s[10:11]
	v_readlane_b32 s10, v241, 19
	v_readlane_b32 s11, v241, 20
	s_add_u32 s20, s10, s8
	s_addc_u32 s21, s11, s9
	s_add_i32 s36, s35, 0x2000
	s_mov_b32 m0, s35
	s_add_u32 s8, s20, 0x40000
	global_load_lds_dwordx4 v134, s[20:21]
	s_mov_b32 m0, s36
	s_addc_u32 s9, s21, 0
	s_add_i32 s37, s35, 0x4000
	global_load_lds_dwordx4 v130, s[20:21]
	s_mov_b32 m0, s37
	s_add_i32 s40, s35, 0x6000
	global_load_lds_dwordx4 v134, s[8:9]
	s_mov_b32 m0, s40
	v_mov_b32_e32 v135, v133
	global_load_lds_dwordx4 v130, s[8:9]
	v_mov_b32_e32 v131, v133
	v_lshl_add_u64 v[6:7], s[22:23], 0, v[132:133]
	s_mov_b32 s41, 0
	v_lshl_add_u64 v[4:5], s[22:23], 0, v[128:129]
	v_lshl_add_u64 v[2:3], s[20:21], 0, v[134:135]
	s_and_b64 vcc, exec, s[62:63]
	v_lshl_add_u64 v[0:1], s[20:21], 0, v[130:131]
	s_cbranch_vccnz .LBB0_829
	s_barrier

; __global__ void __launch_bounds__(512, 2) mega_fwd(Args a) {
	.amdhsa_kernel _Z8mega_fwd4Args
		.amdhsa_group_segment_fixed_size 0
		.amdhsa_private_segment_fixed_size 0
		.amdhsa_kernarg_size 504
		.amdhsa_user_sgpr_count 2
		.amdhsa_user_sgpr_dispatch_ptr 0
		.amdhsa_user_sgpr_queue_ptr 0
		.amdhsa_user_sgpr_kernarg_segment_ptr 1
		.amdhsa_user_sgpr_dispatch_id 0
		.amdhsa_user_sgpr_kernarg_preload_length 0
		.amdhsa_user_sgpr_kernarg_preload_offset 0
		.amdhsa_user_sgpr_private_segment_size 0
		.amdhsa_uses_dynamic_stack 0
		.amdhsa_enable_private_segment 0
		.amdhsa_system_sgpr_workgroup_id_x 1
		.amdhsa_system_sgpr_workgroup_id_y 0
		.amdhsa_system_sgpr_workgroup_id_z 0
		.amdhsa_system_sgpr_workgroup_info 0
		.amdhsa_system_vgpr_workitem_id 2
		.amdhsa_next_free_vgpr 243
		.amdhsa_next_free_sgpr 100
		.amdhsa_accum_offset 244
		.amdhsa_reserve_vcc 1
		.amdhsa_float_round_mode_32 0
		.amdhsa_float_round_mode_16_64 0
		.amdhsa_float_denorm_mode_32 3
		.amdhsa_float_denorm_mode_16_64 3
		.amdhsa_dx10_clamp 1
		.amdhsa_ieee_mode 1
		.amdhsa_fp16_overflow 0
		.amdhsa_tg_split 0
		.amdhsa_exception_fp_ieee_invalid_op 0
		.amdhsa_exception_fp_denorm_src 0
		.amdhsa_exception_fp_ieee_div_zero 0
		.amdhsa_exception_fp_ieee_overflow 0
		.amdhsa_exception_fp_ieee_underflow 0
		.amdhsa_exception_fp_ieee_inexact 0
		.amdhsa_exception_int_div_zero 0
	.end_amdhsa_kernel

; __global__ void __launch_bounds__(512, 2) mega_fwd(Args a) {
amdhsa.kernels:
  - .agpr_count:     0
    .args:
      - .offset:         0
        .size:           248
        .value_kind:     by_value
      - .offset:         248
        .size:           4
        .value_kind:     hidden_block_count_x
      - .offset:         252
        .size:           4
        .value_kind:     hidden_block_count_y
      - .offset:         256
        .size:           4
        .value_kind:     hidden_block_count_z
      - .offset:         260
        .size:           2
        .value_kind:     hidden_group_size_x
      - .offset:         262
        .size:           2
        .value_kind:     hidden_group_size_y
      - .offset:         264
        .size:           2
        .value_kind:     hidden_group_size_z
      - .offset:         266
        .size:           2
        .value_kind:     hidden_remainder_x
      - .offset:         268
        .size:           2
        .value_kind:     hidden_remainder_y
      - .offset:         270
        .size:           2
        .value_kind:     hidden_remainder_z
      - .offset:         288
        .size:           8
        .value_kind:     hidden_global_offset_x
      - .offset:         296
        .size:           8
        .value_kind:     hidden_global_offset_y
      - .offset:         304
        .size:           8
        .value_kind:     hidden_global_offset_z
      - .offset:         312
        .size:           2
        .value_kind:     hidden_grid_dims
      - .offset:         336
        .size:           8
        .value_kind:     hidden_multigrid_sync_arg
      - .offset:         368
        .size:           4
        .value_kind:     hidden_dynamic_lds_size
    .group_segment_fixed_size: 0
    .kernarg_segment_align: 8
    .kernarg_segment_size: 504
    .language:       OpenCL C
    .language_version:
      - 2
      - 0
    .max_flat_workgroup_size: 512
    .name:           _Z8mega_fwd4Args
    .private_segment_fixed_size: 0
    .sgpr_count:     106
    .sgpr_spill_count: 151
    .symbol:         _Z8mega_fwd4Args.kd
    .uniform_work_group_size: 1
    .uses_dynamic_stack: false
    .vgpr_count:     243
    .vgpr_spill_count: 0
    .wavefront_size: 64
